# P1 and P6: older half's compensation barrier moved behind the first epilogue stores
# speedup vs baseline: 1.0104x; 1.0104x over previous
.Lrwp1_exit:
.LBB0_178:
	v_mov_b32_e32 v138, v156
	v_mov_b32_e32 v163, v157
	s_cmp_gt_i32 s62, 9
	s_mov_b64 s[60:61], -1
	s_cbranch_scc0 .LBB0_180
	s_add_i32 s5, s62, -10
	s_lshr_b32 s8, s5, 2
	s_lshl_b64 s[6:7], s[8:9], 26
	s_add_u32 s64, s6, 0xa000000
	s_addc_u32 s65, s7, 0
	s_lshl_b32 s5, s5, 8
	s_and_b32 s5, s5, 0x300
	s_mov_b64 s[60:61], 0

.LBB0_239:
	s_lshl_b64 s[6:7], s[64:65], 1
	s_add_u32 s6, s14, s6
	s_addc_u32 s7, s15, s7
	s_lshl_b32 s4, s4, 8
	s_add_i32 s4, s4, s76
	v_and_or_b32 v114, v138, 7, s4
	v_mad_i64_i32 v[114:115], s[4:5], s60, v114, 0
	v_lshl_add_u64 v[114:115], v[114:115], 1, s[6:7]
	v_cmp_gt_i32_e64 s[4:5], 8, v138
	v_lshl_add_u64 v[114:115], s[8:9], 1, v[114:115]
	v_lshlrev_b32_e32 v116, 4, v163
	v_cndmask_b32_e64 v138, 64, 0, s[4:5]
	v_lshl_add_u64 v[114:115], v[114:115], 0, v[138:139]
	v_ashrrev_i32_e32 v117, 31, v116
	v_lshl_add_u64 v[152:153], v[114:115], 0, v[116:117]
	v_mov_b32_e32 v114, v139
	v_mov_b32_e32 v115, v139
	v_mov_b32_e32 v116, v139
	v_mov_b32_e32 v117, v139
	v_cvt_pk_bf16_f32 v118, v122, v123
	v_cvt_pk_bf16_f32 v119, v126, v127
	v_cvt_pk_bf16_f32 v120, v124, v125
	v_cvt_pk_bf16_f32 v121, v128, v129
	v_mov_b32_e32 v122, v139
	v_mov_b32_e32 v123, v139
	v_mov_b32_dpp v114, v118 row_ror:8 row_mask:0xf bank_mask:0xf
	v_mov_b32_dpp v115, v119 row_ror:8 row_mask:0xf bank_mask:0xf
	v_mov_b32_e32 v124, v139
	v_mov_b32_dpp v116, v120 row_ror:8 row_mask:0xf bank_mask:0xf
	v_mov_b32_e32 v125, v139
	v_mov_b32_dpp v117, v121 row_ror:8 row_mask:0xf bank_mask:0xf
	s_lshl_b32 s8, s60, 4
	v_mov_b32_dpp v122, v148 row_ror:8 row_mask:0xf bank_mask:0xf
	v_mov_b32_dpp v123, v149 row_ror:8 row_mask:0xf bank_mask:0xf
	v_mov_b32_dpp v124, v150 row_ror:8 row_mask:0xf bank_mask:0xf
	v_mov_b32_dpp v125, v151 row_ror:8 row_mask:0xf bank_mask:0xf
	v_cndmask_b32_e64 v114, v114, v148, s[4:5]
	v_cndmask_b32_e64 v115, v115, v149, s[4:5]
	v_cndmask_b32_e64 v116, v116, v150, s[4:5]
	v_cndmask_b32_e64 v117, v117, v151, s[4:5]
	v_cndmask_b32_e64 v118, v118, v122, s[4:5]
	v_cndmask_b32_e64 v119, v119, v123, s[4:5]
	v_cndmask_b32_e64 v120, v120, v124, s[4:5]
	v_cndmask_b32_e64 v121, v121, v125, s[4:5]
	global_store_dwordx4 v[152:153], v[114:117], off nt
	s_bitset1_b32 s98, 16
	s_cmp_lg_u64 s[44:45], 0
	s_cbranch_scc0 .Lp1_nobar
	s_barrier
.Lp1_nobar:
	s_cmp_lt_i32 s49, 2
	s_mov_b64 s[62:63], -1
	v_lshl_add_u64 v[114:115], v[152:153], 0, s[8:9]
	global_store_dwordx4 v[114:115], v[118:121], off nt
	s_bitset1_b32 s98, 17
	s_cbranch_scc1 .LBB0_245
	s_cmp_gt_i32 s49, 2
	s_cbranch_scc0 .LBB0_242
	v_mul_f32_e32 v117, 0xbfb8aa3b, v106
	v_mul_f32_e32 v118, 0xbfb8aa3b, v111
	v_exp_f32_e32 v117, v117
	v_exp_f32_e32 v119, v118
	v_mul_f32_e32 v118, 0xbfb8aa3b, v107
	v_exp_f32_e32 v120, v118
	v_add_f32_e32 v117, 1.0, v117
	v_mul_f32_e32 v121, 0xbfb8aa3b, v108
	v_mul_f32_e32 v122, 0xbfb8aa3b, v113
	v_mul_f32_e32 v116, 0xbfb8aa3b, v110
	v_rcp_f32_e32 v118, v117
	v_add_f32_e32 v117, 1.0, v119
	v_add_f32_e32 v119, 1.0, v120
	v_mul_f32_e32 v120, 0xbfb8aa3b, v112
	v_exp_f32_e32 v121, v121
	v_exp_f32_e32 v123, v122
	v_mul_f32_e32 v122, 0xbfb8aa3b, v109
	v_exp_f32_e32 v116, v116
	v_exp_f32_e32 v120, v120
	v_exp_f32_e32 v124, v122
	v_add_f32_e32 v121, 1.0, v121
	v_add_f32_e32 v116, 1.0, v116
	v_add_f32_e32 v120, 1.0, v120
	v_rcp_f32_e32 v122, v121
	v_add_f32_e32 v121, 1.0, v123
	v_add_f32_e32 v123, 1.0, v124
	v_rcp_f32_e32 v116, v116
	v_rcp_f32_e32 v117, v117
	v_rcp_f32_e32 v119, v119
	v_rcp_f32_e32 v120, v120
	v_rcp_f32_e32 v121, v121
	v_rcp_f32_e32 v123, v123
	s_mov_b64 s[62:63], 0

.Lrwp6_exit:
.LBB0_783:
	s_lshl_b32 s100, s4, 8
	s_add_i32 s100, s100, s59
	s_lshl_b32 s100, s100, 13
	s_lshl_b32 s101, s5, 9
	s_add_u32 s100, s100, s101
	s_add_u32 s100, s100, s8
	s_add_u32 s100, s14, s100
	s_addc_u32 s101, s15, 0
	v_and_b32_e32 v148, 7, v1
	v_lshlrev_b32_e32 v148, 13, v148
	v_lshl_add_u32 v148, v150, 4, v148
	v_and_b32_e32 v149, 8, v1
	v_lshl_add_u32 v148, v149, 3, v148
	v_mov_b32_e32 v248, v148
	v_max_f32_e32 v122, 0, v122
	v_max_f32_e32 v123, 0, v123
	v_max_f32_e32 v124, 0, v124
	v_max_f32_e32 v125, 0, v125
	v_max_f32_e32 v126, 0, v126
	v_max_f32_e32 v127, 0, v127
	v_max_f32_e32 v128, 0, v128
	v_max_f32_e32 v129, 0, v129
	v_max_f32_e32 v114, 0, v114
	v_max_f32_e32 v115, 0, v115
	v_max_f32_e32 v116, 0, v116
	v_max_f32_e32 v117, 0, v117
	v_max_f32_e32 v118, 0, v118
	v_max_f32_e32 v119, 0, v119
	v_max_f32_e32 v120, 0, v120
	v_max_f32_e32 v121, 0, v121
	v_mul_f32_e32 v122, v122, v122
	v_mul_f32_e32 v123, v123, v123
	v_mul_f32_e32 v124, v124, v124
	v_mul_f32_e32 v125, v125, v125
	v_mul_f32_e32 v126, v126, v126
	v_mul_f32_e32 v127, v127, v127
	v_mul_f32_e32 v128, v128, v128
	v_mul_f32_e32 v129, v129, v129
	v_mul_f32_e32 v114, v114, v114
	v_mul_f32_e32 v115, v115, v115
	v_mul_f32_e32 v116, v116, v116
	v_mul_f32_e32 v117, v117, v117
	v_mul_f32_e32 v118, v118, v118
	v_mul_f32_e32 v119, v119, v119
	v_mul_f32_e32 v120, v120, v120
	v_mul_f32_e32 v121, v121, v121
	v_cvt_pk_bf16_f32 v126, v126, v127
	v_cvt_pk_bf16_f32 v127, v128, v129
	v_cvt_pk_bf16_f32 v128, v122, v123
	v_cvt_pk_bf16_f32 v129, v124, v125
	v_cvt_pk_bf16_f32 v118, v118, v119
	v_cvt_pk_bf16_f32 v119, v120, v121
	v_cvt_pk_bf16_f32 v120, v114, v115
	v_cvt_pk_bf16_f32 v121, v116, v117
	v_mov_b32_e32 v122, v126
	v_mov_b32_e32 v123, v127
	v_mov_b32_e32 v124, v128
	v_mov_b32_e32 v125, v129
	v_mov_b32_dpp v126, v118 row_ror:8 row_mask:0xf bank_mask:0xc
	v_mov_b32_dpp v127, v119 row_ror:8 row_mask:0xf bank_mask:0xc
	v_mov_b32_dpp v128, v120 row_ror:8 row_mask:0xf bank_mask:0xc
	v_mov_b32_dpp v129, v121 row_ror:8 row_mask:0xf bank_mask:0xc
	v_mov_b32_dpp v118, v122 row_ror:8 row_mask:0xf bank_mask:0x3
	v_mov_b32_dpp v119, v123 row_ror:8 row_mask:0xf bank_mask:0x3
	v_mov_b32_dpp v120, v124 row_ror:8 row_mask:0xf bank_mask:0x3
	v_mov_b32_dpp v121, v125 row_ror:8 row_mask:0xf bank_mask:0x3
	global_store_dwordx4 v148, v[126:129], s[100:101] nt
	s_add_u32 s100, s100, 0x10000
	s_addc_u32 s101, s101, 0
	global_store_dwordx4 v148, v[118:121], s[100:101] nt
	v_max_f32_e32 v106, 0, v106
	v_max_f32_e32 v107, 0, v107
	v_max_f32_e32 v108, 0, v108
	v_max_f32_e32 v109, 0, v109
	v_max_f32_e32 v110, 0, v110
	v_max_f32_e32 v111, 0, v111
	v_max_f32_e32 v112, 0, v112
	v_max_f32_e32 v113, 0, v113
	v_max_f32_e32 v98, 0, v98
	v_max_f32_e32 v99, 0, v99
	v_max_f32_e32 v100, 0, v100
	v_max_f32_e32 v101, 0, v101
	v_max_f32_e32 v102, 0, v102
	v_max_f32_e32 v103, 0, v103
	v_max_f32_e32 v104, 0, v104
	v_max_f32_e32 v105, 0, v105
	v_mul_f32_e32 v106, v106, v106
	v_mul_f32_e32 v107, v107, v107
	v_mul_f32_e32 v108, v108, v108
	v_mul_f32_e32 v109, v109, v109
	v_mul_f32_e32 v110, v110, v110
	v_mul_f32_e32 v111, v111, v111
	v_mul_f32_e32 v112, v112, v112
	v_mul_f32_e32 v113, v113, v113
	v_mul_f32_e32 v98, v98, v98
	v_mul_f32_e32 v99, v99, v99
	v_mul_f32_e32 v100, v100, v100
	v_mul_f32_e32 v101, v101, v101
	v_mul_f32_e32 v102, v102, v102
	v_mul_f32_e32 v103, v103, v103
	v_mul_f32_e32 v104, v104, v104
	v_mul_f32_e32 v105, v105, v105
	v_cvt_pk_bf16_f32 v110, v110, v111
	v_cvt_pk_bf16_f32 v111, v112, v113
	v_cvt_pk_bf16_f32 v112, v106, v107
	v_cvt_pk_bf16_f32 v113, v108, v109
	v_cvt_pk_bf16_f32 v102, v102, v103
	v_cvt_pk_bf16_f32 v103, v104, v105
	v_cvt_pk_bf16_f32 v104, v98, v99
	v_cvt_pk_bf16_f32 v105, v100, v101
	v_mov_b32_e32 v106, v110
	v_mov_b32_e32 v107, v111
	v_mov_b32_e32 v108, v112
	v_mov_b32_e32 v109, v113
	v_mov_b32_dpp v110, v102 row_ror:8 row_mask:0xf bank_mask:0xc
	v_mov_b32_dpp v111, v103 row_ror:8 row_mask:0xf bank_mask:0xc
	v_mov_b32_dpp v112, v104 row_ror:8 row_mask:0xf bank_mask:0xc
	v_mov_b32_dpp v113, v105 row_ror:8 row_mask:0xf bank_mask:0xc
	v_mov_b32_dpp v102, v106 row_ror:8 row_mask:0xf bank_mask:0x3
	v_mov_b32_dpp v103, v107 row_ror:8 row_mask:0xf bank_mask:0x3
	v_mov_b32_dpp v104, v108 row_ror:8 row_mask:0xf bank_mask:0x3
	v_mov_b32_dpp v105, v109 row_ror:8 row_mask:0xf bank_mask:0x3
	s_add_u32 s100, s100, 0x10000
	s_addc_u32 s101, s101, 0
	global_store_dwordx4 v148, v[110:113], s[100:101] nt
	s_add_u32 s100, s100, 0x10000
	s_addc_u32 s101, s101, 0
	global_store_dwordx4 v148, v[102:105], s[100:101] nt
	s_and_b64 vcc, exec, s[36:37]
	s_cbranch_vccz .Lepi6_nobar
	s_barrier
.Lepi6_nobar:
	v_max_f32_e32 v90, 0, v90
	v_max_f32_e32 v91, 0, v91
	v_max_f32_e32 v92, 0, v92
	v_max_f32_e32 v93, 0, v93
	v_max_f32_e32 v94, 0, v94
	v_max_f32_e32 v95, 0, v95
	v_max_f32_e32 v96, 0, v96
	v_max_f32_e32 v97, 0, v97
	v_max_f32_e32 v82, 0, v82
	v_max_f32_e32 v83, 0, v83
	v_max_f32_e32 v84, 0, v84
	v_max_f32_e32 v85, 0, v85
	v_max_f32_e32 v86, 0, v86
	v_max_f32_e32 v87, 0, v87
	v_max_f32_e32 v88, 0, v88
	v_max_f32_e32 v89, 0, v89
	v_mul_f32_e32 v90, v90, v90
	v_mul_f32_e32 v91, v91, v91
	v_mul_f32_e32 v92, v92, v92
	v_mul_f32_e32 v93, v93, v93
	v_mul_f32_e32 v94, v94, v94
	v_mul_f32_e32 v95, v95, v95
	v_mul_f32_e32 v96, v96, v96
	v_mul_f32_e32 v97, v97, v97
	v_mul_f32_e32 v82, v82, v82
	v_mul_f32_e32 v83, v83, v83
	v_mul_f32_e32 v84, v84, v84
	v_mul_f32_e32 v85, v85, v85
	v_mul_f32_e32 v86, v86, v86
	v_mul_f32_e32 v87, v87, v87
	v_mul_f32_e32 v88, v88, v88
	v_mul_f32_e32 v89, v89, v89
	v_cvt_pk_bf16_f32 v94, v94, v95
	v_cvt_pk_bf16_f32 v95, v96, v97
	v_cvt_pk_bf16_f32 v96, v90, v91
	v_cvt_pk_bf16_f32 v97, v92, v93
	v_cvt_pk_bf16_f32 v86, v86, v87
	v_cvt_pk_bf16_f32 v87, v88, v89
	v_cvt_pk_bf16_f32 v88, v82, v83
	v_cvt_pk_bf16_f32 v89, v84, v85
	v_mov_b32_e32 v90, v94
	v_mov_b32_e32 v91, v95
	v_mov_b32_e32 v92, v96
	v_mov_b32_e32 v93, v97
	v_mov_b32_dpp v94, v86 row_ror:8 row_mask:0xf bank_mask:0xc
	v_mov_b32_dpp v95, v87 row_ror:8 row_mask:0xf bank_mask:0xc
	v_mov_b32_dpp v96, v88 row_ror:8 row_mask:0xf bank_mask:0xc
	v_mov_b32_dpp v97, v89 row_ror:8 row_mask:0xf bank_mask:0xc
	v_mov_b32_dpp v86, v90 row_ror:8 row_mask:0xf bank_mask:0x3
	v_mov_b32_dpp v87, v91 row_ror:8 row_mask:0xf bank_mask:0x3
	v_mov_b32_dpp v88, v92 row_ror:8 row_mask:0xf bank_mask:0x3
	v_mov_b32_dpp v89, v93 row_ror:8 row_mask:0xf bank_mask:0x3
	s_add_u32 s100, s100, 0x10000
	s_addc_u32 s101, s101, 0
	global_store_dwordx4 v148, v[94:97], s[100:101] nt
	s_add_u32 s100, s100, 0x10000
	s_addc_u32 s101, s101, 0
	global_store_dwordx4 v148, v[86:89], s[100:101] nt
	v_max_f32_e32 v74, 0, v74
	v_max_f32_e32 v75, 0, v75
	v_max_f32_e32 v76, 0, v76
	v_max_f32_e32 v77, 0, v77
	v_max_f32_e32 v78, 0, v78
	v_max_f32_e32 v79, 0, v79
	v_max_f32_e32 v80, 0, v80
	v_max_f32_e32 v81, 0, v81
	v_max_f32_e32 v66, 0, v66
	v_max_f32_e32 v67, 0, v67
	v_max_f32_e32 v68, 0, v68
	v_max_f32_e32 v69, 0, v69
	v_max_f32_e32 v70, 0, v70
	v_max_f32_e32 v71, 0, v71
	v_max_f32_e32 v72, 0, v72
	v_max_f32_e32 v73, 0, v73
	v_mul_f32_e32 v74, v74, v74
	v_mul_f32_e32 v75, v75, v75
	v_mul_f32_e32 v76, v76, v76
	v_mul_f32_e32 v77, v77, v77
	v_mul_f32_e32 v78, v78, v78
	v_mul_f32_e32 v79, v79, v79
	v_mul_f32_e32 v80, v80, v80
	v_mul_f32_e32 v81, v81, v81
	v_mul_f32_e32 v66, v66, v66
	v_mul_f32_e32 v67, v67, v67
	v_mul_f32_e32 v68, v68, v68
	v_mul_f32_e32 v69, v69, v69
	v_mul_f32_e32 v70, v70, v70
	v_mul_f32_e32 v71, v71, v71
	v_mul_f32_e32 v72, v72, v72
	v_mul_f32_e32 v73, v73, v73
	v_cvt_pk_bf16_f32 v78, v78, v79
	v_cvt_pk_bf16_f32 v79, v80, v81
	v_cvt_pk_bf16_f32 v80, v74, v75
	v_cvt_pk_bf16_f32 v81, v76, v77
	v_cvt_pk_bf16_f32 v70, v70, v71
	v_cvt_pk_bf16_f32 v71, v72, v73
	v_cvt_pk_bf16_f32 v72, v66, v67
	v_cvt_pk_bf16_f32 v73, v68, v69
	v_mov_b32_e32 v74, v78
	v_mov_b32_e32 v75, v79
	v_mov_b32_e32 v76, v80
	v_mov_b32_e32 v77, v81
	v_mov_b32_dpp v78, v70 row_ror:8 row_mask:0xf bank_mask:0xc
	v_mov_b32_dpp v79, v71 row_ror:8 row_mask:0xf bank_mask:0xc
	v_mov_b32_dpp v80, v72 row_ror:8 row_mask:0xf bank_mask:0xc
	v_mov_b32_dpp v81, v73 row_ror:8 row_mask:0xf bank_mask:0xc
	v_mov_b32_dpp v70, v74 row_ror:8 row_mask:0xf bank_mask:0x3
	v_mov_b32_dpp v71, v75 row_ror:8 row_mask:0xf bank_mask:0x3
	v_mov_b32_dpp v72, v76 row_ror:8 row_mask:0xf bank_mask:0x3
	v_mov_b32_dpp v73, v77 row_ror:8 row_mask:0xf bank_mask:0x3
	s_add_u32 s100, s100, 0x10000
	s_addc_u32 s101, s101, 0
	global_store_dwordx4 v148, v[78:81], s[100:101] nt
	s_add_u32 s100, s100, 0x10000
	s_addc_u32 s101, s101, 0
	global_store_dwordx4 v148, v[70:73], s[100:101] nt
	v_max_f32_e32 v58, 0, v58
	v_max_f32_e32 v59, 0, v59
	v_max_f32_e32 v60, 0, v60
	v_max_f32_e32 v61, 0, v61
	v_max_f32_e32 v62, 0, v62
	v_max_f32_e32 v63, 0, v63
	v_max_f32_e32 v64, 0, v64
	v_max_f32_e32 v65, 0, v65
	v_max_f32_e32 v50, 0, v50
	v_max_f32_e32 v51, 0, v51
	v_max_f32_e32 v52, 0, v52
	v_max_f32_e32 v53, 0, v53
	v_max_f32_e32 v54, 0, v54
	v_max_f32_e32 v55, 0, v55
	v_max_f32_e32 v56, 0, v56
	v_max_f32_e32 v57, 0, v57
	v_mul_f32_e32 v58, v58, v58
	v_mul_f32_e32 v59, v59, v59
	v_mul_f32_e32 v60, v60, v60
	v_mul_f32_e32 v61, v61, v61
	v_mul_f32_e32 v62, v62, v62
	v_mul_f32_e32 v63, v63, v63
	v_mul_f32_e32 v64, v64, v64
	v_mul_f32_e32 v65, v65, v65
	v_mul_f32_e32 v50, v50, v50
	v_mul_f32_e32 v51, v51, v51
	v_mul_f32_e32 v52, v52, v52
	v_mul_f32_e32 v53, v53, v53
	v_mul_f32_e32 v54, v54, v54
	v_mul_f32_e32 v55, v55, v55
	v_mul_f32_e32 v56, v56, v56
	v_mul_f32_e32 v57, v57, v57
	v_cvt_pk_bf16_f32 v62, v62, v63
	v_cvt_pk_bf16_f32 v63, v64, v65
	v_cvt_pk_bf16_f32 v64, v58, v59
	v_cvt_pk_bf16_f32 v65, v60, v61
	v_cvt_pk_bf16_f32 v54, v54, v55
	v_cvt_pk_bf16_f32 v55, v56, v57
	v_cvt_pk_bf16_f32 v56, v50, v51
	v_cvt_pk_bf16_f32 v57, v52, v53
	v_mov_b32_e32 v58, v62
	v_mov_b32_e32 v59, v63
	v_mov_b32_e32 v60, v64
	v_mov_b32_e32 v61, v65
	v_mov_b32_dpp v62, v54 row_ror:8 row_mask:0xf bank_mask:0xc
	v_mov_b32_dpp v63, v55 row_ror:8 row_mask:0xf bank_mask:0xc
	v_mov_b32_dpp v64, v56 row_ror:8 row_mask:0xf bank_mask:0xc
	v_mov_b32_dpp v65, v57 row_ror:8 row_mask:0xf bank_mask:0xc
	v_mov_b32_dpp v54, v58 row_ror:8 row_mask:0xf bank_mask:0x3
	v_mov_b32_dpp v55, v59 row_ror:8 row_mask:0xf bank_mask:0x3
	v_mov_b32_dpp v56, v60 row_ror:8 row_mask:0xf bank_mask:0x3
	v_mov_b32_dpp v57, v61 row_ror:8 row_mask:0xf bank_mask:0x3
	s_add_u32 s100, s100, 0x90000
	s_addc_u32 s101, s101, 0
	global_store_dwordx4 v148, v[62:65], s[100:101] nt
	s_add_u32 s100, s100, 0x10000
	s_addc_u32 s101, s101, 0
	global_store_dwordx4 v148, v[54:57], s[100:101] nt
	v_max_f32_e32 v42, 0, v42
	v_max_f32_e32 v43, 0, v43
	v_max_f32_e32 v44, 0, v44
	v_max_f32_e32 v45, 0, v45
	v_max_f32_e32 v46, 0, v46
	v_max_f32_e32 v47, 0, v47
	v_max_f32_e32 v48, 0, v48
	v_max_f32_e32 v49, 0, v49
	v_max_f32_e32 v34, 0, v34
	v_max_f32_e32 v35, 0, v35
	v_max_f32_e32 v36, 0, v36
	v_max_f32_e32 v37, 0, v37
	v_max_f32_e32 v38, 0, v38
	v_max_f32_e32 v39, 0, v39
	v_max_f32_e32 v40, 0, v40
	v_max_f32_e32 v41, 0, v41
	v_mul_f32_e32 v42, v42, v42
	v_mul_f32_e32 v43, v43, v43
	v_mul_f32_e32 v44, v44, v44
	v_mul_f32_e32 v45, v45, v45
	v_mul_f32_e32 v46, v46, v46
	v_mul_f32_e32 v47, v47, v47
	v_mul_f32_e32 v48, v48, v48
	v_mul_f32_e32 v49, v49, v49
	v_mul_f32_e32 v34, v34, v34
	v_mul_f32_e32 v35, v35, v35
	v_mul_f32_e32 v36, v36, v36
	v_mul_f32_e32 v37, v37, v37
	v_mul_f32_e32 v38, v38, v38
	v_mul_f32_e32 v39, v39, v39
	v_mul_f32_e32 v40, v40, v40
	v_mul_f32_e32 v41, v41, v41
	v_cvt_pk_bf16_f32 v46, v46, v47
	v_cvt_pk_bf16_f32 v47, v48, v49
	v_cvt_pk_bf16_f32 v48, v42, v43
	v_cvt_pk_bf16_f32 v49, v44, v45
	v_cvt_pk_bf16_f32 v38, v38, v39
	v_cvt_pk_bf16_f32 v39, v40, v41
	v_cvt_pk_bf16_f32 v40, v34, v35
	v_cvt_pk_bf16_f32 v41, v36, v37
	v_mov_b32_e32 v42, v46
	v_mov_b32_e32 v43, v47
	v_mov_b32_e32 v44, v48
	v_mov_b32_e32 v45, v49
	v_mov_b32_dpp v46, v38 row_ror:8 row_mask:0xf bank_mask:0xc
	v_mov_b32_dpp v47, v39 row_ror:8 row_mask:0xf bank_mask:0xc
	v_mov_b32_dpp v48, v40 row_ror:8 row_mask:0xf bank_mask:0xc
	v_mov_b32_dpp v49, v41 row_ror:8 row_mask:0xf bank_mask:0xc
	v_mov_b32_dpp v38, v42 row_ror:8 row_mask:0xf bank_mask:0x3
	v_mov_b32_dpp v39, v43 row_ror:8 row_mask:0xf bank_mask:0x3
	v_mov_b32_dpp v40, v44 row_ror:8 row_mask:0xf bank_mask:0x3
	v_mov_b32_dpp v41, v45 row_ror:8 row_mask:0xf bank_mask:0x3
	s_add_u32 s100, s100, 0x10000
	s_addc_u32 s101, s101, 0
	global_store_dwordx4 v148, v[46:49], s[100:101] nt
	s_add_u32 s100, s100, 0x10000
	s_addc_u32 s101, s101, 0
	v_mov_b32_e32 v228, v38
	v_mov_b32_e32 v229, v39
	v_mov_b32_e32 v230, v40
	v_mov_b32_e32 v231, v41
	v_max_f32_e32 v26, 0, v26
	v_max_f32_e32 v27, 0, v27
	v_max_f32_e32 v28, 0, v28
	v_max_f32_e32 v29, 0, v29
	v_max_f32_e32 v30, 0, v30
	v_max_f32_e32 v31, 0, v31
	v_max_f32_e32 v32, 0, v32
	v_max_f32_e32 v33, 0, v33
	v_max_f32_e32 v18, 0, v18
	v_max_f32_e32 v19, 0, v19
	v_max_f32_e32 v20, 0, v20
	v_max_f32_e32 v21, 0, v21
	v_max_f32_e32 v22, 0, v22
	v_max_f32_e32 v23, 0, v23
	v_max_f32_e32 v24, 0, v24
	v_max_f32_e32 v25, 0, v25
	v_mul_f32_e32 v26, v26, v26
	v_mul_f32_e32 v27, v27, v27
	v_mul_f32_e32 v28, v28, v28
	v_mul_f32_e32 v29, v29, v29
	v_mul_f32_e32 v30, v30, v30
	v_mul_f32_e32 v31, v31, v31
	v_mul_f32_e32 v32, v32, v32
	v_mul_f32_e32 v33, v33, v33
	v_mul_f32_e32 v18, v18, v18
	v_mul_f32_e32 v19, v19, v19
	v_mul_f32_e32 v20, v20, v20
	v_mul_f32_e32 v21, v21, v21
	v_mul_f32_e32 v22, v22, v22
	v_mul_f32_e32 v23, v23, v23
	v_mul_f32_e32 v24, v24, v24
	v_mul_f32_e32 v25, v25, v25
	v_cvt_pk_bf16_f32 v30, v30, v31
	v_cvt_pk_bf16_f32 v31, v32, v33
	v_cvt_pk_bf16_f32 v32, v26, v27
	v_cvt_pk_bf16_f32 v33, v28, v29
	v_cvt_pk_bf16_f32 v22, v22, v23
	v_cvt_pk_bf16_f32 v23, v24, v25
	v_cvt_pk_bf16_f32 v24, v18, v19
	v_cvt_pk_bf16_f32 v25, v20, v21
	v_mov_b32_e32 v26, v30
	v_mov_b32_e32 v27, v31
	v_mov_b32_e32 v28, v32
	v_mov_b32_e32 v29, v33
	v_mov_b32_dpp v30, v22 row_ror:8 row_mask:0xf bank_mask:0xc
	v_mov_b32_dpp v31, v23 row_ror:8 row_mask:0xf bank_mask:0xc
	v_mov_b32_dpp v32, v24 row_ror:8 row_mask:0xf bank_mask:0xc
	v_mov_b32_dpp v33, v25 row_ror:8 row_mask:0xf bank_mask:0xc
	v_mov_b32_dpp v22, v26 row_ror:8 row_mask:0xf bank_mask:0x3
	v_mov_b32_dpp v23, v27 row_ror:8 row_mask:0xf bank_mask:0x3
	v_mov_b32_dpp v24, v28 row_ror:8 row_mask:0xf bank_mask:0x3
	v_mov_b32_dpp v25, v29 row_ror:8 row_mask:0xf bank_mask:0x3
	v_mov_b32_e32 v232, v30
	v_mov_b32_e32 v233, v31
	v_mov_b32_e32 v234, v32
	v_mov_b32_e32 v235, v33
	v_mov_b32_e32 v236, v22
	v_mov_b32_e32 v237, v23
	v_mov_b32_e32 v238, v24
	v_mov_b32_e32 v239, v25
	v_max_f32_e32 v10, 0, v10
	v_max_f32_e32 v11, 0, v11
	v_max_f32_e32 v12, 0, v12
	v_max_f32_e32 v13, 0, v13
	v_max_f32_e32 v14, 0, v14
	v_max_f32_e32 v15, 0, v15
	v_max_f32_e32 v16, 0, v16
	v_max_f32_e32 v17, 0, v17
	v_max_f32_e32 v2, 0, v2
	v_max_f32_e32 v3, 0, v3
	v_max_f32_e32 v4, 0, v4
	v_max_f32_e32 v5, 0, v5
	v_max_f32_e32 v6, 0, v6
	v_max_f32_e32 v7, 0, v7
	v_max_f32_e32 v8, 0, v8
	v_max_f32_e32 v9, 0, v9
	v_mul_f32_e32 v10, v10, v10
	v_mul_f32_e32 v11, v11, v11
	v_mul_f32_e32 v12, v12, v12
	v_mul_f32_e32 v13, v13, v13
	v_mul_f32_e32 v14, v14, v14
	v_mul_f32_e32 v15, v15, v15
	v_mul_f32_e32 v16, v16, v16
	v_mul_f32_e32 v17, v17, v17
	v_mul_f32_e32 v2, v2, v2
	v_mul_f32_e32 v3, v3, v3
	v_mul_f32_e32 v4, v4, v4
	v_mul_f32_e32 v5, v5, v5
	v_mul_f32_e32 v6, v6, v6
	v_mul_f32_e32 v7, v7, v7
	v_mul_f32_e32 v8, v8, v8
	v_mul_f32_e32 v9, v9, v9
	v_cvt_pk_bf16_f32 v14, v14, v15
	v_cvt_pk_bf16_f32 v15, v16, v17
	v_cvt_pk_bf16_f32 v16, v10, v11
	v_cvt_pk_bf16_f32 v17, v12, v13
	v_cvt_pk_bf16_f32 v6, v6, v7
	v_cvt_pk_bf16_f32 v7, v8, v9
	v_cvt_pk_bf16_f32 v8, v2, v3
	v_cvt_pk_bf16_f32 v9, v4, v5
	v_mov_b32_e32 v10, v14
	v_mov_b32_e32 v11, v15
	v_mov_b32_e32 v12, v16
	v_mov_b32_e32 v13, v17
	v_mov_b32_dpp v14, v6 row_ror:8 row_mask:0xf bank_mask:0xc
	v_mov_b32_dpp v15, v7 row_ror:8 row_mask:0xf bank_mask:0xc
	v_mov_b32_dpp v16, v8 row_ror:8 row_mask:0xf bank_mask:0xc
	v_mov_b32_dpp v17, v9 row_ror:8 row_mask:0xf bank_mask:0xc
	v_mov_b32_dpp v6, v10 row_ror:8 row_mask:0xf bank_mask:0x3
	v_mov_b32_dpp v7, v11 row_ror:8 row_mask:0xf bank_mask:0x3
	v_mov_b32_dpp v8, v12 row_ror:8 row_mask:0xf bank_mask:0x3
	v_mov_b32_dpp v9, v13 row_ror:8 row_mask:0xf bank_mask:0x3
	v_mov_b32_e32 v240, v14
	v_mov_b32_e32 v241, v15
	v_mov_b32_e32 v242, v16
	v_mov_b32_e32 v243, v17
	v_mov_b32_e32 v244, v6
	v_mov_b32_e32 v245, v7
	v_mov_b32_e32 v246, v8
	v_mov_b32_e32 v247, v9
	s_mov_b32 s99, 0
	s_andn2_b64 vcc, exec, s[0:1]
	s_mov_b64 s[0:1], -1
	s_mov_b32 s98, 1
	s_cbranch_vccnz .LBB0_772
	s_andn2_b64 vcc, exec, s[10:11]
	s_cbranch_vccnz .LBB0_771
	s_barrier
	s_branch .LBB0_771
